# v21 + redundant cooperative-groups grid.sync after the prologue barrier removed (layout re-padded) + 4-byte placement phase of the SwiGLU and QKV GEMM K-loops flipped
# baseline (speedup 1.0000x reference)
; #define GSYNC() xcd_barrier(xbar)
; __global__ void __launch_bounds__(NWAVES * 64, 2) mega_fwd(Args a) {
;     ...
;     GSYNC();
;     grid.sync();
.LBB0_192:
	s_or_b64 exec, exec, s[0:1]
	s_waitcnt lgkmcnt(0)
	v_lshrrev_b32_e32 v1, 20, v0
	v_lshrrev_b32_e32 v0, 10, v0
	v_or_b32_e32 v0, v0, v1
	s_movk_i32 s0, 0x3ff
	v_and_or_b32 v0, v0, s0, v228
	v_cmp_eq_u32_e32 vcc, 0, v0
	s_barrier
	s_barrier
	s_and_saveexec_b64 s[0:1], vcc
	s_branch .LBB0_202
	s_nop 0
	s_nop 0
	s_nop 0
	s_nop 0
	s_nop 0
	s_nop 0
	s_nop 0
	s_nop 0
	s_nop 0
	s_nop 0
	s_nop 0
	s_nop 0
	s_nop 0
	s_nop 0
	s_nop 0
	s_nop 0
	s_nop 0
	s_nop 0
	s_nop 0
	s_nop 0
	s_nop 0
	s_nop 0
	s_nop 0
	s_nop 0
	s_nop 0
	s_nop 0
	s_nop 0
	s_nop 0
	s_nop 0
	s_nop 0
	s_nop 0
	s_nop 0
	s_nop 0
	s_nop 0
	s_nop 0
	s_nop 0
	s_nop 0
	s_nop 0
	s_nop 0
	s_nop 0
	s_nop 0
	s_nop 0
	s_nop 0
	s_nop 0
	s_nop 0
	s_nop 0
	s_nop 0
	s_nop 0
	s_nop 0
	s_nop 0
	s_nop 0
	s_nop 0
	s_nop 0
	s_nop 0
	s_nop 0
	s_nop 0
	s_nop 0
	s_nop 0
	s_nop 0
	s_nop 0
	s_nop 0
	s_nop 0
	s_nop 0
	s_nop 0
	s_nop 0
	s_nop 0
	s_nop 0
	s_nop 0
	s_nop 0
	s_nop 0
	s_nop 0
	s_nop 0
	s_nop 0

; #define PG8_STAGE(bufoff, gbase, voff) do { _Pragma("unroll") for (int _i = 0; _i < 2; ++_i) \
;         __builtin_amdgcn_global_load_lds((const unsigned*)((const char*)(gbase) + (voff)[_i]), (PG8_LAS unsigned*)(lds + (bufoff) + ldsw + _i * 8192), 16, 0, 0); } while (0)
; #define PG8_LDA(dst, b, h) do { _Pragma("unroll") for (int m = 0; m < 4; ++m) _Pragma("unroll") for (int k = 0; k < 2; ++k) dst[m][k] = *(const PG8_LAS bf16x8*)(lds + PG8_SA(b, h) + aoff + m * 2048 + k * 1024); } while (0)
; #define PG8_LDB(dst, b, h) do { _Pragma("unroll") for (int n = 0; n < 2; ++n) _Pragma("unroll") for (int k = 0; k < 2; ++k) dst[n][k] = *(const PG8_LAS bf16x8*)(lds + PG8_SB(b, h) + boff + n * 2048 + k * 1024); } while (0)
; #define PG8_WAIT_V(n) asm volatile("s_waitcnt vmcnt(" #n ")" ::: "memory")
; #define PG8_WAIT_L(n) asm volatile("s_waitcnt lgkmcnt(" #n ")" ::: "memory")
; template <class Epi, class Sched, bool ALIGN_EPI = false, bool SP2 = false>
; __device__ __forceinline__ void gemm_phase(PG8_LAS unsigned char* lds, const Gemm g, const Sched& S, const Epi& E) {
;     ...
;         const char* nA = has_next ? (const char*)g.A + (size_t)nxt.pm * tstepA + (size_t)(nxt.pn >> 2) * g.aselb : cA; const char* nB = has_next ? (const char*)g.Bt + (size_t)nxt.pn * tstep : cB;
;         for (int t = 0; t < nt; t += 2) {
;             if constexpr (Epi::MID) { if (t == (nt >> 1)) E.mid(acc, cur, wr, wc, fr, fq); }
;             const bool last = (t == nt - 2);
;             const char* a1 = cA + (size_t)(t + 1) * kstep;
;             const char* a2 = last ? nA : cA + (size_t)(t + 2) * kstep; const char* b2 = last ? nB : cB + (size_t)(t + 2) * kstep;
;             const char* a3 = a2 + kstep; const char* b3 = b2 + kstep;
;             if (last && has_next) S.a_ready(nxt);
;             if constexpr (SP2) {
;             PG8_LDB(B0, 0, 0); PG8_LDB(B1, 0, 1); PG8_SCHED; PG8_LDA(At, 0, 0); PG8_STAGE(PG8_SA(1, 1), a1 + hstepA, voffA);
;             PG8_WAIT_V(8); PG8_WAIT_L(0); PG8_BAR; PG8_MMA(0, 0, At, B0); PG8_MMA(0, 1, At, B1); PG8_BAR; PG8_SCHED;
;     ...
; #pragma unroll
;         for (int a = 0; a < 2; ++a)
; #pragma unroll
;             for (int b = 0; b < 2; ++b)
; #pragma unroll
;                 for (int m = 0; m < 4; ++m)
; #pragma unroll
;                     for (int n = 0; n < 2; ++n) acc[a][b][m][n] = (f32x4){0.f, 0.f, 0.f, 0.f};
;         cur = nxt; cA = nA; cB = nB; ++ui;
.LBB0_854:
	s_ashr_i32 s43, s42, 31
	s_lshl_b64 s[44:45], s[42:43], 19
	s_add_u32 s44, s30, s44
	s_addc_u32 s45, s31, s45
	s_and_b64 s[46:47], s[52:53], exec
	s_cselect_b32 s39, s45, s49
	s_cselect_b32 s41, s44, s48
	s_ashr_i32 s27, s26, 31
	s_lshl_b64 s[46:47], s[26:27], 19
	s_add_u32 s46, s54, s46
	s_addc_u32 s47, s55, s47
	s_and_b64 s[52:53], s[52:53], exec
	s_cselect_b32 s27, s47, s51
	s_cselect_b32 s43, s46, s50
	s_add_u32 s48, s48, 0x40080
	s_addc_u32 s49, s49, 0
	s_add_u32 s66, s50, 0x100
	v_mov_b32_e32 v2, 0
	s_addc_u32 s67, s51, 0
	s_mov_b32 s68, -2
	v_mov_b32_e32 v3, v2
	v_mov_b32_e32 v4, v2
	v_mov_b32_e32 v5, v2
	v_mov_b32_e32 v6, v2
	v_mov_b32_e32 v7, v2
	v_mov_b32_e32 v8, v2
	v_mov_b32_e32 v9, v2
	v_mov_b32_e32 v18, v2
	v_mov_b32_e32 v19, v2
	v_mov_b32_e32 v20, v2
	v_mov_b32_e32 v21, v2
	v_mov_b32_e32 v22, v2
	v_mov_b32_e32 v23, v2
	v_mov_b32_e32 v24, v2
	v_mov_b32_e32 v25, v2
	v_mov_b32_e32 v50, v2
	v_mov_b32_e32 v51, v2
	v_mov_b32_e32 v52, v2
	v_mov_b32_e32 v53, v2
	v_mov_b32_e32 v54, v2
	v_mov_b32_e32 v55, v2
	v_mov_b32_e32 v56, v2
	v_mov_b32_e32 v57, v2
	v_mov_b32_e32 v66, v2
	v_mov_b32_e32 v67, v2
	v_mov_b32_e32 v68, v2
	v_mov_b32_e32 v69, v2
	v_mov_b32_e32 v70, v2
	v_mov_b32_e32 v71, v2
	v_mov_b32_e32 v72, v2
	v_mov_b32_e32 v73, v2
	v_mov_b32_e32 v10, v2
	v_mov_b32_e32 v11, v2
	v_mov_b32_e32 v12, v2
	v_mov_b32_e32 v13, v2
	v_mov_b32_e32 v14, v2
	v_mov_b32_e32 v15, v2
	v_mov_b32_e32 v16, v2
	v_mov_b32_e32 v17, v2
	v_mov_b32_e32 v26, v2
	v_mov_b32_e32 v27, v2
	v_mov_b32_e32 v28, v2
	v_mov_b32_e32 v29, v2
	v_mov_b32_e32 v30, v2
	v_mov_b32_e32 v31, v2
	v_mov_b32_e32 v32, v2
	v_mov_b32_e32 v33, v2
	v_mov_b32_e32 v58, v2
	v_mov_b32_e32 v59, v2
	v_mov_b32_e32 v60, v2
	v_mov_b32_e32 v61, v2
	v_mov_b32_e32 v62, v2
	v_mov_b32_e32 v63, v2
	v_mov_b32_e32 v64, v2
	v_mov_b32_e32 v65, v2
	v_mov_b32_e32 v74, v2
	v_mov_b32_e32 v75, v2
	v_mov_b32_e32 v76, v2
	v_mov_b32_e32 v77, v2
	v_mov_b32_e32 v78, v2
	v_mov_b32_e32 v79, v2
	v_mov_b32_e32 v80, v2
	v_mov_b32_e32 v81, v2
	v_mov_b32_e32 v82, v2
	v_mov_b32_e32 v83, v2
	v_mov_b32_e32 v84, v2
	v_mov_b32_e32 v85, v2
	v_mov_b32_e32 v86, v2
	v_mov_b32_e32 v87, v2
	v_mov_b32_e32 v88, v2
	v_mov_b32_e32 v89, v2
	v_mov_b32_e32 v98, v2
	v_mov_b32_e32 v99, v2
	v_mov_b32_e32 v100, v2
	v_mov_b32_e32 v101, v2
	v_mov_b32_e32 v102, v2
	v_mov_b32_e32 v103, v2
	v_mov_b32_e32 v104, v2
	v_mov_b32_e32 v105, v2
	v_mov_b32_e32 v114, v2
	v_mov_b32_e32 v115, v2
	v_mov_b32_e32 v116, v2
	v_mov_b32_e32 v117, v2
	v_mov_b32_e32 v118, v2
	v_mov_b32_e32 v119, v2
	v_mov_b32_e32 v120, v2
	v_mov_b32_e32 v121, v2
	v_mov_b32_e32 v130, v2
	v_mov_b32_e32 v131, v2
	v_mov_b32_e32 v132, v2
	v_mov_b32_e32 v133, v2
	v_mov_b32_e32 v134, v2
	v_mov_b32_e32 v135, v2
	v_mov_b32_e32 v136, v2
	v_mov_b32_e32 v137, v2
	v_mov_b32_e32 v90, v2
	v_mov_b32_e32 v91, v2
	v_mov_b32_e32 v92, v2
	v_mov_b32_e32 v93, v2
	v_mov_b32_e32 v94, v2
	v_mov_b32_e32 v95, v2
	v_mov_b32_e32 v96, v2
	v_mov_b32_e32 v97, v2
	v_mov_b32_e32 v106, v2
	v_mov_b32_e32 v107, v2
	v_mov_b32_e32 v108, v2
	v_mov_b32_e32 v109, v2
	v_mov_b32_e32 v110, v2
	v_mov_b32_e32 v111, v2
	v_mov_b32_e32 v112, v2
	v_mov_b32_e32 v113, v2
	v_mov_b32_e32 v122, v2
	v_mov_b32_e32 v123, v2
	v_mov_b32_e32 v124, v2
	v_mov_b32_e32 v125, v2
	v_mov_b32_e32 v126, v2
	v_mov_b32_e32 v127, v2
	v_mov_b32_e32 v128, v2
	v_mov_b32_e32 v129, v2
	v_mov_b32_e32 v138, v2
	v_mov_b32_e32 v139, v2
	v_mov_b32_e32 v140, v2
	v_mov_b32_e32 v141, v2
	v_mov_b32_e32 v142, v2
	v_mov_b32_e32 v143, v2
	v_mov_b32_e32 v144, v2
	v_mov_b32_e32 v145, v2
	s_nop 0
.LBB0_855:
	s_add_u32 s34, s48, 0xfffc0080
	s_addc_u32 s35, s49, -1
	s_add_i32 s69, 0, 0x10000
	s_cmp_eq_u32 s68, 12
	s_cselect_b32 s53, s39, s35
	s_cselect_b32 s52, s41, s34
	s_cselect_b32 s51, s27, s67
	s_cselect_b32 s50, s43, s66
	s_add_i32 s34, 0, 0x14000
	v_add_u32_e32 v46, s69, v191
	v_add_u32_e32 v174, s34, v191
	ds_read_b128 v[34:37], v46
	ds_read_b128 v[38:41], v46 offset:1024
	ds_read_b128 v[42:45], v46 offset:2048
	ds_read_b128 v[46:49], v46 offset:3072
	ds_read_b128 v[146:149], v174
	ds_read_b128 v[150:153], v174 offset:1024
	ds_read_b128 v[154:157], v174 offset:2048
	ds_read_b128 v[174:177], v174 offset:3072
	v_lshl_add_u64 v[214:215], s[48:49], 0, v[170:171]
	s_add_i32 m0, s56, 0xc000
	ds_read_b128 v[178:181], v193
	ds_read_b128 v[182:185], v193 offset:1024
	ds_read_b128 v[186:189], v193 offset:2048
	ds_read_b128 v[194:197], v193 offset:3072
	ds_read_b128 v[198:201], v193 offset:4096
	ds_read_b128 v[202:205], v193 offset:5120
	ds_read_b128 v[206:209], v193 offset:6144
	ds_read_b128 v[210:213], v193 offset:7168
	global_load_lds_dwordx4 v[214:215], off
	v_lshl_add_u64 v[214:215], s[48:49], 0, v[172:173]
	s_add_i32 m0, s56, 0xe000
	s_nop 0
	global_load_lds_dwordx4 v[214:215], off
	s_waitcnt vmcnt(8)
	s_waitcnt lgkmcnt(0)
	s_barrier
; #define PG8_STAGE(bufoff, gbase, voff) do { _Pragma("unroll") for (int _i = 0; _i < 2; ++_i) \
;         __builtin_amdgcn_global_load_lds((const unsigned*)((const char*)(gbase) + (voff)[_i]), (PG8_LAS unsigned*)(lds + (bufoff) + ldsw + _i * 8192), 16, 0, 0); } while (0)
; #define PG8_LDA(dst, b, h) do { _Pragma("unroll") for (int m = 0; m < 4; ++m) _Pragma("unroll") for (int k = 0; k < 2; ++k) dst[m][k] = *(const PG8_LAS bf16x8*)(lds + PG8_SA(b, h) + aoff + m * 2048 + k * 1024); } while (0)
; #define PG8_MMA(ai, bj, At, Bt) do { __builtin_amdgcn_s_setprio(1); _Pragma("unroll") for (int m = 0; m < 4; ++m) _Pragma("unroll") for (int n = 0; n < 2; ++n) _Pragma("unroll") for (int k = 0; k < 2; ++k) \
;         acc[ai][bj][m][n] = __builtin_amdgcn_mfma_f32_16x16x32_bf16(Bt[n][k], At[m][k], acc[ai][bj][m][n], 0, 0, 0); __builtin_amdgcn_s_setprio(0); } while (0)
; #define PG8_WAIT_V(n) asm volatile("s_waitcnt vmcnt(" #n ")" ::: "memory")
; #define PG8_WAIT_L(n) asm volatile("s_waitcnt lgkmcnt(" #n ")" ::: "memory")
; #define PG8_BAR __builtin_amdgcn_s_barrier()
; #define PG8_SCHED __builtin_amdgcn_sched_barrier(0)
; template <class Epi, class Sched, bool ALIGN_EPI = false, bool SP2 = false>
; __device__ __forceinline__ void gemm_phase(PG8_LAS unsigned char* lds, const Gemm g, const Sched& S, const Epi& E) {
;     ...
;             PG8_WAIT_V(8); PG8_WAIT_L(0); PG8_BAR; PG8_MMA(0, 0, At, B0); PG8_MMA(0, 1, At, B1); PG8_BAR; PG8_SCHED;
;             PG8_LDA(At, 0, 1); PG8_STAGE(PG8_SB(0, 0), b2, voffB); PG8_STAGE(PG8_SB(0, 1), b2 + hstep, voffB); PG8_STAGE(PG8_SA(0, 0), a2, voffA);
;             PG8_WAIT_V(8); PG8_WAIT_L(0); PG8_BAR; PG8_MMA(1, 0, At, B0); PG8_MMA(1, 1, At, B1); PG8_BAR; PG8_SCHED;
	s_setprio 1
	s_waitcnt lgkmcnt(0)
	v_mfma_f32_16x16x32_bf16 v[142:145], v[34:37], v[178:181], v[142:145]
	v_mfma_f32_16x16x32_bf16 v[138:141], v[42:45], v[178:181], v[138:141]
	v_mfma_f32_16x16x32_bf16 v[126:129], v[34:37], v[186:189], v[126:129]
	v_mfma_f32_16x16x32_bf16 v[122:125], v[42:45], v[186:189], v[122:125]
	v_mfma_f32_16x16x32_bf16 v[110:113], v[34:37], v[198:201], v[110:113]
	v_mfma_f32_16x16x32_bf16 v[106:109], v[42:45], v[198:201], v[106:109]
	v_mfma_f32_16x16x32_bf16 v[94:97], v[34:37], v[206:209], v[94:97]
	v_mfma_f32_16x16x32_bf16 v[90:93], v[42:45], v[206:209], v[90:93]
	v_mfma_f32_16x16x32_bf16 v[142:145], v[38:41], v[182:185], v[142:145]
	v_mfma_f32_16x16x32_bf16 v[138:141], v[46:49], v[182:185], v[138:141]
	v_mfma_f32_16x16x32_bf16 v[126:129], v[38:41], v[194:197], v[126:129]
	v_mfma_f32_16x16x32_bf16 v[122:125], v[46:49], v[194:197], v[122:125]
	v_mfma_f32_16x16x32_bf16 v[110:113], v[38:41], v[202:205], v[110:113]
	v_mfma_f32_16x16x32_bf16 v[106:109], v[46:49], v[202:205], v[106:109]
	v_mfma_f32_16x16x32_bf16 v[94:97], v[38:41], v[210:213], v[94:97]
	v_mfma_f32_16x16x32_bf16 v[90:93], v[46:49], v[210:213], v[90:93]
	s_setprio 0
	s_setprio 1
	v_mfma_f32_16x16x32_bf16 v[134:137], v[146:149], v[178:181], v[134:137]
	v_mfma_f32_16x16x32_bf16 v[130:133], v[154:157], v[178:181], v[130:133]
	v_mfma_f32_16x16x32_bf16 v[118:121], v[146:149], v[186:189], v[118:121]
	v_mfma_f32_16x16x32_bf16 v[114:117], v[154:157], v[186:189], v[114:117]
	v_mfma_f32_16x16x32_bf16 v[102:105], v[146:149], v[198:201], v[102:105]
	v_mfma_f32_16x16x32_bf16 v[98:101], v[154:157], v[198:201], v[98:101]
	v_mfma_f32_16x16x32_bf16 v[86:89], v[146:149], v[206:209], v[86:89]
	v_mfma_f32_16x16x32_bf16 v[82:85], v[154:157], v[206:209], v[82:85]
	v_mfma_f32_16x16x32_bf16 v[134:137], v[150:153], v[182:185], v[134:137]
	v_mfma_f32_16x16x32_bf16 v[130:133], v[174:177], v[182:185], v[130:133]
	v_mfma_f32_16x16x32_bf16 v[118:121], v[150:153], v[194:197], v[118:121]
	v_mfma_f32_16x16x32_bf16 v[114:117], v[174:177], v[194:197], v[114:117]
	v_mfma_f32_16x16x32_bf16 v[102:105], v[150:153], v[202:205], v[102:105]
	v_mfma_f32_16x16x32_bf16 v[98:101], v[174:177], v[202:205], v[98:101]
	v_mfma_f32_16x16x32_bf16 v[86:89], v[150:153], v[210:213], v[86:89]
	v_mfma_f32_16x16x32_bf16 v[82:85], v[174:177], v[210:213], v[82:85]
	s_setprio 0
	s_barrier
	s_add_i32 s35, s69, s22
	v_lshl_add_u64 v[214:215], s[50:51], 0, v[160:161]
	s_mov_b32 m0, s35
	ds_read_b128 v[178:181], v193 offset:16384
	ds_read_b128 v[182:185], v193 offset:17408
	ds_read_b128 v[186:189], v193 offset:18432
	ds_read_b128 v[194:197], v193 offset:19456
	ds_read_b128 v[198:201], v193 offset:20480
	ds_read_b128 v[202:205], v193 offset:21504
	ds_read_b128 v[206:209], v193 offset:22528
	ds_read_b128 v[210:213], v193 offset:23552
	global_load_lds_dwordx4 v[214:215], off
	s_add_i32 m0, s35, 0x2000
	s_add_u32 s70, s50, 0x40000
	v_lshl_add_u64 v[216:217], s[50:51], 0, v[164:165]
	s_addc_u32 s71, s51, 0
	s_add_i32 s34, s34, s22
	global_load_lds_dwordx4 v[216:217], off
	v_lshl_add_u64 v[218:219], s[70:71], 0, v[160:161]
	s_mov_b32 m0, s34
	v_lshl_add_u64 v[220:221], s[52:53], 0, v[162:163]
	global_load_lds_dwordx4 v[218:219], off
	v_lshl_add_u64 v[218:219], s[70:71], 0, v[164:165]
	s_add_i32 m0, s34, 0x2000
	s_nop 0
	global_load_lds_dwordx4 v[218:219], off
	v_lshl_add_u64 v[218:219], s[52:53], 0, v[158:159]
	s_mov_b32 m0, s56
	s_nop 0
	global_load_lds_dwordx4 v[218:219], off
	s_mov_b32 m0, s57
	s_nop 0
	global_load_lds_dwordx4 v[220:221], off
	s_waitcnt vmcnt(8)
	s_waitcnt lgkmcnt(0)
	s_barrier
	s_setprio 1
	s_waitcnt lgkmcnt(0)
	v_mfma_f32_16x16x32_bf16 v[78:81], v[34:37], v[178:181], v[78:81]
	v_mfma_f32_16x16x32_bf16 v[74:77], v[42:45], v[178:181], v[74:77]
	v_mfma_f32_16x16x32_bf16 v[62:65], v[34:37], v[186:189], v[62:65]
	v_mfma_f32_16x16x32_bf16 v[58:61], v[42:45], v[186:189], v[58:61]
	v_mfma_f32_16x16x32_bf16 v[30:33], v[34:37], v[198:201], v[30:33]
	v_mfma_f32_16x16x32_bf16 v[26:29], v[42:45], v[198:201], v[26:29]
	v_mfma_f32_16x16x32_bf16 v[14:17], v[34:37], v[206:209], v[14:17]
	v_mfma_f32_16x16x32_bf16 v[10:13], v[42:45], v[206:209], v[10:13]
	v_mfma_f32_16x16x32_bf16 v[78:81], v[38:41], v[182:185], v[78:81]
	v_mfma_f32_16x16x32_bf16 v[74:77], v[46:49], v[182:185], v[74:77]
	v_mfma_f32_16x16x32_bf16 v[62:65], v[38:41], v[194:197], v[62:65]
	v_mfma_f32_16x16x32_bf16 v[58:61], v[46:49], v[194:197], v[58:61]
	v_mfma_f32_16x16x32_bf16 v[30:33], v[38:41], v[202:205], v[30:33]
	v_mfma_f32_16x16x32_bf16 v[26:29], v[46:49], v[202:205], v[26:29]
	v_mfma_f32_16x16x32_bf16 v[14:17], v[38:41], v[210:213], v[14:17]
	v_mfma_f32_16x16x32_bf16 v[10:13], v[46:49], v[210:213], v[10:13]
	s_setprio 0
	s_setprio 1
	v_mfma_f32_16x16x32_bf16 v[22:25], v[146:149], v[198:201], v[22:25]
	v_mfma_f32_16x16x32_bf16 v[18:21], v[154:157], v[198:201], v[18:21]
	v_mfma_f32_16x16x32_bf16 v[6:9], v[146:149], v[206:209], v[6:9]
	v_mfma_f32_16x16x32_bf16 v[2:5], v[154:157], v[206:209], v[2:5]
	v_mfma_f32_16x16x32_bf16 v[34:37], v[146:149], v[178:181], v[70:73]
	v_mfma_f32_16x16x32_bf16 v[38:41], v[154:157], v[178:181], v[66:69]
	v_mfma_f32_16x16x32_bf16 v[42:45], v[146:149], v[186:189], v[54:57]
	v_mfma_f32_16x16x32_bf16 v[46:49], v[154:157], v[186:189], v[50:53]
	v_mfma_f32_16x16x32_bf16 v[22:25], v[150:153], v[202:205], v[22:25]
	v_mfma_f32_16x16x32_bf16 v[18:21], v[174:177], v[202:205], v[18:21]
	v_mfma_f32_16x16x32_bf16 v[6:9], v[150:153], v[210:213], v[6:9]
	v_mfma_f32_16x16x32_bf16 v[2:5], v[174:177], v[210:213], v[2:5]
	v_mfma_f32_16x16x32_bf16 v[34:37], v[150:153], v[182:185], v[34:37]
	v_mfma_f32_16x16x32_bf16 v[38:41], v[174:177], v[182:185], v[38:41]
	v_mfma_f32_16x16x32_bf16 v[42:45], v[150:153], v[194:197], v[42:45]
	v_mfma_f32_16x16x32_bf16 v[46:49], v[174:177], v[194:197], v[46:49]
	s_setprio 0
	s_barrier
; #define PG8_STAGE(bufoff, gbase, voff) do { _Pragma("unroll") for (int _i = 0; _i < 2; ++_i) \
;         __builtin_amdgcn_global_load_lds((const unsigned*)((const char*)(gbase) + (voff)[_i]), (PG8_LAS unsigned*)(lds + (bufoff) + ldsw + _i * 8192), 16, 0, 0); } while (0)
; #define PG8_LDA(dst, b, h) do { _Pragma("unroll") for (int m = 0; m < 4; ++m) _Pragma("unroll") for (int k = 0; k < 2; ++k) dst[m][k] = *(const PG8_LAS bf16x8*)(lds + PG8_SA(b, h) + aoff + m * 2048 + k * 1024); } while (0)
; #define PG8_LDB(dst, b, h) do { _Pragma("unroll") for (int n = 0; n < 2; ++n) _Pragma("unroll") for (int k = 0; k < 2; ++k) dst[n][k] = *(const PG8_LAS bf16x8*)(lds + PG8_SB(b, h) + boff + n * 2048 + k * 1024); } while (0)
; #define PG8_MMA(ai, bj, At, Bt) do { __builtin_amdgcn_s_setprio(1); _Pragma("unroll") for (int m = 0; m < 4; ++m) _Pragma("unroll") for (int n = 0; n < 2; ++n) _Pragma("unroll") for (int k = 0; k < 2; ++k) \
;         acc[ai][bj][m][n] = __builtin_amdgcn_mfma_f32_16x16x32_bf16(Bt[n][k], At[m][k], acc[ai][bj][m][n], 0, 0, 0); __builtin_amdgcn_s_setprio(0); } while (0)
; #define PG8_WAIT_V(n) asm volatile("s_waitcnt vmcnt(" #n ")" ::: "memory")
; #define PG8_WAIT_L(n) asm volatile("s_waitcnt lgkmcnt(" #n ")" ::: "memory")
; #define PG8_BAR __builtin_amdgcn_s_barrier()
; #define PG8_SCHED __builtin_amdgcn_sched_barrier(0)
; template <class Epi, class Sched, bool ALIGN_EPI = false, bool SP2 = false>
; __device__ __forceinline__ void gemm_phase(PG8_LAS unsigned char* lds, const Gemm g, const Sched& S, const Epi& E) {
;     ...
;             PG8_LDB(B0, 1, 0); PG8_LDB(B1, 1, 1); PG8_SCHED; PG8_LDA(At, 1, 0); PG8_STAGE(PG8_SA(0, 1), a2 + hstepA, voffA);
;             PG8_WAIT_V(8); PG8_WAIT_L(0); PG8_BAR; PG8_MMA(0, 0, At, B0); PG8_MMA(0, 1, At, B1); PG8_BAR; PG8_SCHED;
	s_add_i32 s34, 0, 0x18000
	s_add_i32 s35, 0, 0x1c000
	v_add_u32_e32 v70, s34, v191
	v_add_u32_e32 v174, s35, v191
	ds_read_b128 v[50:53], v70
	ds_read_b128 v[54:57], v70 offset:1024
	ds_read_b128 v[66:69], v70 offset:2048
	ds_read_b128 v[70:73], v70 offset:3072
	ds_read_b128 v[146:149], v174
	ds_read_b128 v[150:153], v174 offset:1024
	ds_read_b128 v[154:157], v174 offset:2048
	ds_read_b128 v[174:177], v174 offset:3072
	s_add_u32 s52, s52, 0x40000
	s_addc_u32 s53, s53, 0
	s_mov_b32 m0, s58
	v_lshl_add_u64 v[222:223], s[52:53], 0, v[158:159]
	ds_read_b128 v[178:181], v193 offset:32768
	ds_read_b128 v[182:185], v193 offset:33792
	ds_read_b128 v[186:189], v193 offset:34816
	ds_read_b128 v[194:197], v193 offset:35840
	ds_read_b128 v[198:201], v193 offset:36864
	ds_read_b128 v[202:205], v193 offset:37888
	ds_read_b128 v[206:209], v193 offset:38912
	ds_read_b128 v[210:213], v193 offset:39936
	global_load_lds_dwordx4 v[222:223], off
	v_lshl_add_u64 v[222:223], s[52:53], 0, v[162:163]
	s_mov_b32 m0, s59
	s_nop 0
	global_load_lds_dwordx4 v[222:223], off
	s_waitcnt vmcnt(8)
	s_waitcnt lgkmcnt(0)
	s_barrier
	s_setprio 1
	s_waitcnt lgkmcnt(0)
	v_mfma_f32_16x16x32_bf16 v[142:145], v[50:53], v[178:181], v[142:145]
	v_mfma_f32_16x16x32_bf16 v[138:141], v[66:69], v[178:181], v[138:141]
	v_mfma_f32_16x16x32_bf16 v[126:129], v[50:53], v[186:189], v[126:129]
	v_mfma_f32_16x16x32_bf16 v[122:125], v[66:69], v[186:189], v[122:125]
	v_mfma_f32_16x16x32_bf16 v[110:113], v[50:53], v[198:201], v[110:113]
	v_mfma_f32_16x16x32_bf16 v[106:109], v[66:69], v[198:201], v[106:109]
	v_mfma_f32_16x16x32_bf16 v[94:97], v[50:53], v[206:209], v[94:97]
	v_mfma_f32_16x16x32_bf16 v[90:93], v[66:69], v[206:209], v[90:93]
	v_mfma_f32_16x16x32_bf16 v[142:145], v[54:57], v[182:185], v[142:145]
	v_mfma_f32_16x16x32_bf16 v[138:141], v[70:73], v[182:185], v[138:141]
	v_mfma_f32_16x16x32_bf16 v[126:129], v[54:57], v[194:197], v[126:129]
	v_mfma_f32_16x16x32_bf16 v[122:125], v[70:73], v[194:197], v[122:125]
	v_mfma_f32_16x16x32_bf16 v[110:113], v[54:57], v[202:205], v[110:113]
	v_mfma_f32_16x16x32_bf16 v[106:109], v[70:73], v[202:205], v[106:109]
	v_mfma_f32_16x16x32_bf16 v[94:97], v[54:57], v[210:213], v[94:97]
	v_mfma_f32_16x16x32_bf16 v[90:93], v[70:73], v[210:213], v[90:93]
	s_setprio 0
	s_setprio 1
	v_mfma_f32_16x16x32_bf16 v[134:137], v[146:149], v[178:181], v[134:137]
	v_mfma_f32_16x16x32_bf16 v[130:133], v[154:157], v[178:181], v[130:133]
	v_mfma_f32_16x16x32_bf16 v[118:121], v[146:149], v[186:189], v[118:121]
	v_mfma_f32_16x16x32_bf16 v[114:117], v[154:157], v[186:189], v[114:117]
	v_mfma_f32_16x16x32_bf16 v[102:105], v[146:149], v[198:201], v[102:105]
	v_mfma_f32_16x16x32_bf16 v[98:101], v[154:157], v[198:201], v[98:101]
	v_mfma_f32_16x16x32_bf16 v[86:89], v[146:149], v[206:209], v[86:89]
	v_mfma_f32_16x16x32_bf16 v[82:85], v[154:157], v[206:209], v[82:85]
	v_mfma_f32_16x16x32_bf16 v[134:137], v[150:153], v[182:185], v[134:137]
	v_mfma_f32_16x16x32_bf16 v[130:133], v[174:177], v[182:185], v[130:133]
	v_mfma_f32_16x16x32_bf16 v[118:121], v[150:153], v[194:197], v[118:121]
	v_mfma_f32_16x16x32_bf16 v[114:117], v[174:177], v[194:197], v[114:117]
	v_mfma_f32_16x16x32_bf16 v[102:105], v[150:153], v[202:205], v[102:105]
	v_mfma_f32_16x16x32_bf16 v[98:101], v[174:177], v[202:205], v[98:101]
	v_mfma_f32_16x16x32_bf16 v[86:89], v[150:153], v[210:213], v[86:89]
	v_mfma_f32_16x16x32_bf16 v[82:85], v[174:177], v[210:213], v[82:85]
	s_setprio 0
	s_barrier
; #define PG8_STAGE(bufoff, gbase, voff) do { _Pragma("unroll") for (int _i = 0; _i < 2; ++_i) \
;         __builtin_amdgcn_global_load_lds((const unsigned*)((const char*)(gbase) + (voff)[_i]), (PG8_LAS unsigned*)(lds + (bufoff) + ldsw + _i * 8192), 16, 0, 0); } while (0)
; #define PG8_LDA(dst, b, h) do { _Pragma("unroll") for (int m = 0; m < 4; ++m) _Pragma("unroll") for (int k = 0; k < 2; ++k) dst[m][k] = *(const PG8_LAS bf16x8*)(lds + PG8_SA(b, h) + aoff + m * 2048 + k * 1024); } while (0)
; #define PG8_MMA(ai, bj, At, Bt) do { __builtin_amdgcn_s_setprio(1); _Pragma("unroll") for (int m = 0; m < 4; ++m) _Pragma("unroll") for (int n = 0; n < 2; ++n) _Pragma("unroll") for (int k = 0; k < 2; ++k) \
;         acc[ai][bj][m][n] = __builtin_amdgcn_mfma_f32_16x16x32_bf16(Bt[n][k], At[m][k], acc[ai][bj][m][n], 0, 0, 0); __builtin_amdgcn_s_setprio(0); } while (0)
; #define PG8_WAIT_V(n) asm volatile("s_waitcnt vmcnt(" #n ")" ::: "memory")
; #define PG8_WAIT_L(n) asm volatile("s_waitcnt lgkmcnt(" #n ")" ::: "memory")
; #define PG8_BAR __builtin_amdgcn_s_barrier()
; #define PG8_SCHED __builtin_amdgcn_sched_barrier(0)
; template <class Epi, class Sched, bool ALIGN_EPI = false, bool SP2 = false>
; __device__ __forceinline__ void gemm_phase(PG8_LAS unsigned char* lds, const Gemm g, const Sched& S, const Epi& E) {
;     ...
;             PG8_LDA(At, 1, 1); PG8_STAGE(PG8_SB(1, 0), b3, voffB); PG8_STAGE(PG8_SB(1, 1), b3 + hstep, voffB); PG8_STAGE(PG8_SA(1, 0), a3, voffA);
;             PG8_WAIT_V(8); PG8_WAIT_L(0); PG8_BAR; PG8_MMA(1, 0, At, B0); PG8_MMA(1, 1, At, B1); PG8_BAR; PG8_SCHED;
	s_add_i32 s34, s34, s22
	v_lshl_add_u64 v[214:215], v[214:215], 0, s[12:13]
	s_mov_b32 m0, s34
	ds_read_b128 v[178:181], v193 offset:49152
	ds_read_b128 v[182:185], v193 offset:50176
	ds_read_b128 v[186:189], v193 offset:51200
	ds_read_b128 v[194:197], v193 offset:52224
	ds_read_b128 v[198:201], v193 offset:53248
	ds_read_b128 v[202:205], v193 offset:54272
	ds_read_b128 v[206:209], v193 offset:55296
	ds_read_b128 v[210:213], v193 offset:56320
	global_load_lds_dwordx4 v[214:215], off
	s_add_i32 m0, s34, 0x2000
	s_add_u32 s50, s50, 0x40080
	v_lshl_add_u64 v[214:215], v[216:217], 0, s[12:13]
	s_addc_u32 s51, s51, 0
	s_add_i32 s34, s35, s22
	global_load_lds_dwordx4 v[214:215], off
	v_lshl_add_u64 v[214:215], s[50:51], 0, v[160:161]
	s_mov_b32 m0, s34
	s_nop 0
	global_load_lds_dwordx4 v[214:215], off
	v_lshl_add_u64 v[214:215], s[50:51], 0, v[164:165]
	s_add_i32 m0, s34, 0x2000
	s_nop 0
	global_load_lds_dwordx4 v[214:215], off
	v_lshl_add_u64 v[214:215], v[218:219], 0, s[12:13]
	s_mov_b32 m0, s60
	s_nop 0
	global_load_lds_dwordx4 v[214:215], off
	v_lshl_add_u64 v[214:215], v[220:221], 0, s[12:13]
	s_mov_b32 m0, s61
	s_nop 0
	global_load_lds_dwordx4 v[214:215], off
	s_waitcnt vmcnt(8)
	s_waitcnt lgkmcnt(0)
	s_barrier
	s_setprio 1
	s_waitcnt lgkmcnt(0)
	v_mfma_f32_16x16x32_bf16 v[78:81], v[50:53], v[178:181], v[78:81]
	v_mfma_f32_16x16x32_bf16 v[74:77], v[66:69], v[178:181], v[74:77]
	v_mfma_f32_16x16x32_bf16 v[62:65], v[50:53], v[186:189], v[62:65]
	v_mfma_f32_16x16x32_bf16 v[58:61], v[66:69], v[186:189], v[58:61]
	v_mfma_f32_16x16x32_bf16 v[30:33], v[50:53], v[198:201], v[30:33]
	v_mfma_f32_16x16x32_bf16 v[26:29], v[66:69], v[198:201], v[26:29]
	v_mfma_f32_16x16x32_bf16 v[14:17], v[50:53], v[206:209], v[14:17]
	v_mfma_f32_16x16x32_bf16 v[10:13], v[66:69], v[206:209], v[10:13]
	v_mfma_f32_16x16x32_bf16 v[78:81], v[54:57], v[182:185], v[78:81]
	v_mfma_f32_16x16x32_bf16 v[74:77], v[70:73], v[182:185], v[74:77]
	v_mfma_f32_16x16x32_bf16 v[62:65], v[54:57], v[194:197], v[62:65]
	v_mfma_f32_16x16x32_bf16 v[58:61], v[70:73], v[194:197], v[58:61]
	v_mfma_f32_16x16x32_bf16 v[30:33], v[54:57], v[202:205], v[30:33]
	v_mfma_f32_16x16x32_bf16 v[26:29], v[70:73], v[202:205], v[26:29]
	v_mfma_f32_16x16x32_bf16 v[14:17], v[54:57], v[210:213], v[14:17]
	v_mfma_f32_16x16x32_bf16 v[10:13], v[70:73], v[210:213], v[10:13]
	s_setprio 0
	s_setprio 1
	v_mfma_f32_16x16x32_bf16 v[34:37], v[146:149], v[178:181], v[34:37]
	v_mfma_f32_16x16x32_bf16 v[70:73], v[150:153], v[182:185], v[34:37]
	v_mfma_f32_16x16x32_bf16 v[34:37], v[154:157], v[178:181], v[38:41]
	v_mfma_f32_16x16x32_bf16 v[66:69], v[174:177], v[182:185], v[34:37]
	v_mfma_f32_16x16x32_bf16 v[34:37], v[146:149], v[186:189], v[42:45]
	v_mfma_f32_16x16x32_bf16 v[54:57], v[150:153], v[194:197], v[34:37]
	v_mfma_f32_16x16x32_bf16 v[34:37], v[154:157], v[186:189], v[46:49]
	v_mfma_f32_16x16x32_bf16 v[22:25], v[146:149], v[198:201], v[22:25]
	v_mfma_f32_16x16x32_bf16 v[18:21], v[154:157], v[198:201], v[18:21]
	v_mfma_f32_16x16x32_bf16 v[6:9], v[146:149], v[206:209], v[6:9]
	v_mfma_f32_16x16x32_bf16 v[2:5], v[154:157], v[206:209], v[2:5]
	v_mfma_f32_16x16x32_bf16 v[50:53], v[174:177], v[194:197], v[34:37]
	v_mfma_f32_16x16x32_bf16 v[22:25], v[150:153], v[202:205], v[22:25]
	v_mfma_f32_16x16x32_bf16 v[18:21], v[174:177], v[202:205], v[18:21]
	v_mfma_f32_16x16x32_bf16 v[6:9], v[150:153], v[210:213], v[6:9]
	v_mfma_f32_16x16x32_bf16 v[2:5], v[174:177], v[210:213], v[2:5]
	s_setprio 0
	s_barrier
	s_add_i32 s68, s68, 2
	s_add_u32 s48, s48, 0x100
	s_addc_u32 s49, s49, 0
	s_add_u32 s66, s66, 0x100
	s_addc_u32 s67, s67, 0
	s_cmp_gt_u32 s68, 13
	s_cbranch_scc0 .LBB0_855
	s_nop 0
	s_and_b64 vcc, exec, s[6:7]
	s_cbranch_vccz .LBB0_858
	s_barrier

; #define PG8_STAGE(bufoff, gbase, voff) do { _Pragma("unroll") for (int _i = 0; _i < 2; ++_i) \
;         __builtin_amdgcn_global_load_lds((const unsigned*)((const char*)(gbase) + (voff)[_i]), (PG8_LAS unsigned*)(lds + (bufoff) + ldsw + _i * 8192), 16, 0, 0); } while (0)
; #define PG8_LDA(dst, b, h) do { _Pragma("unroll") for (int m = 0; m < 4; ++m) _Pragma("unroll") for (int k = 0; k < 2; ++k) dst[m][k] = *(const PG8_LAS bf16x8*)(lds + PG8_SA(b, h) + aoff + m * 2048 + k * 1024); } while (0)
; #define PG8_LDB(dst, b, h) do { _Pragma("unroll") for (int n = 0; n < 2; ++n) _Pragma("unroll") for (int k = 0; k < 2; ++k) dst[n][k] = *(const PG8_LAS bf16x8*)(lds + PG8_SB(b, h) + boff + n * 2048 + k * 1024); } while (0)
; #define PG8_WAIT_V(n) asm volatile("s_waitcnt vmcnt(" #n ")" ::: "memory")
; #define PG8_WAIT_L(n) asm volatile("s_waitcnt lgkmcnt(" #n ")" ::: "memory")
; template <class Epi, class Sched, bool ALIGN_EPI = false, bool SP2 = false>
; __device__ __forceinline__ void gemm_phase(PG8_LAS unsigned char* lds, const Gemm g, const Sched& S, const Epi& E) {
;     ...
;         const char* nA = has_next ? (const char*)g.A + (size_t)nxt.pm * tstepA + (size_t)(nxt.pn >> 2) * g.aselb : cA; const char* nB = has_next ? (const char*)g.Bt + (size_t)nxt.pn * tstep : cB;
;         for (int t = 0; t < nt; t += 2) {
;             if constexpr (Epi::MID) { if (t == (nt >> 1)) E.mid(acc, cur, wr, wc, fr, fq); }
;             const bool last = (t == nt - 2);
;             const char* a1 = cA + (size_t)(t + 1) * kstep;
;             const char* a2 = last ? nA : cA + (size_t)(t + 2) * kstep; const char* b2 = last ? nB : cB + (size_t)(t + 2) * kstep;
;             const char* a3 = a2 + kstep; const char* b3 = b2 + kstep;
;             if (last && has_next) S.a_ready(nxt);
;             if constexpr (SP2) {
;             PG8_LDB(B0, 0, 0); PG8_LDB(B1, 0, 1); PG8_SCHED; PG8_LDA(At, 0, 0); PG8_STAGE(PG8_SA(1, 1), a1 + hstepA, voffA);
;             PG8_WAIT_V(8); PG8_WAIT_L(0); PG8_BAR; PG8_MMA(0, 0, At, B0); PG8_MMA(0, 1, At, B1); PG8_BAR; PG8_SCHED;
;     ...
; #pragma unroll
;         for (int a = 0; a < 2; ++a)
; #pragma unroll
;             for (int b = 0; b < 2; ++b)
; #pragma unroll
;                 for (int m = 0; m < 4; ++m)
; #pragma unroll
;                     for (int n = 0; n < 2; ++n) acc[a][b][m][n] = (f32x4){0.f, 0.f, 0.f, 0.f};
;         cur = nxt; cA = nA; cB = nB; ++ui;
.LBB0_1148:
	s_ashr_i32 s37, s36, 31
	s_lshl_b64 s[38:39], s[36:37], 19
	s_add_u32 s38, s30, s38
	s_addc_u32 s39, s31, s39
	s_and_b64 s[40:41], s[50:51], exec
	s_cselect_b32 s37, s39, s47
	s_cselect_b32 s62, s38, s46
	s_ashr_i32 s27, s26, 31
	s_lshl_b64 s[40:41], s[26:27], 19
	s_add_u32 s40, s52, s40
	s_addc_u32 s41, s53, s41
	s_and_b64 s[50:51], s[50:51], exec
	s_cselect_b32 s27, s41, s49
	s_cselect_b32 s63, s40, s48
	s_add_u32 s46, s46, 0x40080
	s_addc_u32 s47, s47, 0
	s_add_u32 s64, s48, 0x100
	v_mov_b32_e32 v2, 0
	s_addc_u32 s65, s49, 0
	s_mov_b32 s66, -2
	v_mov_b32_e32 v3, v2
	v_mov_b32_e32 v4, v2
	v_mov_b32_e32 v5, v2
	v_mov_b32_e32 v10, v2
	v_mov_b32_e32 v11, v2
	v_mov_b32_e32 v12, v2
	v_mov_b32_e32 v13, v2
	v_mov_b32_e32 v18, v2
	v_mov_b32_e32 v19, v2
	v_mov_b32_e32 v20, v2
	v_mov_b32_e32 v21, v2
	v_mov_b32_e32 v26, v2
	v_mov_b32_e32 v27, v2
	v_mov_b32_e32 v28, v2
	v_mov_b32_e32 v29, v2
	v_mov_b32_e32 v34, v2
	v_mov_b32_e32 v35, v2
	v_mov_b32_e32 v36, v2
	v_mov_b32_e32 v37, v2
	v_mov_b32_e32 v42, v2
	v_mov_b32_e32 v43, v2
	v_mov_b32_e32 v44, v2
	v_mov_b32_e32 v45, v2
	v_mov_b32_e32 v50, v2
	v_mov_b32_e32 v51, v2
	v_mov_b32_e32 v52, v2
	v_mov_b32_e32 v53, v2
	v_mov_b32_e32 v58, v2
	v_mov_b32_e32 v59, v2
	v_mov_b32_e32 v60, v2
	v_mov_b32_e32 v61, v2
	v_mov_b32_e32 v6, v2
	v_mov_b32_e32 v7, v2
	v_mov_b32_e32 v8, v2
	v_mov_b32_e32 v9, v2
	v_mov_b32_e32 v14, v2
	v_mov_b32_e32 v15, v2
	v_mov_b32_e32 v16, v2
	v_mov_b32_e32 v17, v2
	v_mov_b32_e32 v22, v2
	v_mov_b32_e32 v23, v2
	v_mov_b32_e32 v24, v2
	v_mov_b32_e32 v25, v2
	v_mov_b32_e32 v30, v2
	v_mov_b32_e32 v31, v2
	v_mov_b32_e32 v32, v2
	v_mov_b32_e32 v33, v2
	v_mov_b32_e32 v38, v2
	v_mov_b32_e32 v39, v2
	v_mov_b32_e32 v40, v2
	v_mov_b32_e32 v41, v2
	v_mov_b32_e32 v46, v2
	v_mov_b32_e32 v47, v2
	v_mov_b32_e32 v48, v2
	v_mov_b32_e32 v49, v2
	v_mov_b32_e32 v54, v2
	v_mov_b32_e32 v55, v2
	v_mov_b32_e32 v56, v2
	v_mov_b32_e32 v57, v2
	v_mov_b32_e32 v62, v2
	v_mov_b32_e32 v63, v2
	v_mov_b32_e32 v64, v2
	v_mov_b32_e32 v65, v2
	v_mov_b32_e32 v66, v2
	v_mov_b32_e32 v67, v2
	v_mov_b32_e32 v68, v2
	v_mov_b32_e32 v69, v2
	v_mov_b32_e32 v74, v2
	v_mov_b32_e32 v75, v2
	v_mov_b32_e32 v76, v2
	v_mov_b32_e32 v77, v2
	v_mov_b32_e32 v82, v2
	v_mov_b32_e32 v83, v2
	v_mov_b32_e32 v84, v2
	v_mov_b32_e32 v85, v2
	v_mov_b32_e32 v90, v2
	v_mov_b32_e32 v91, v2
	v_mov_b32_e32 v92, v2
	v_mov_b32_e32 v93, v2
	v_mov_b32_e32 v98, v2
	v_mov_b32_e32 v99, v2
	v_mov_b32_e32 v100, v2
	v_mov_b32_e32 v101, v2
	v_mov_b32_e32 v106, v2
	v_mov_b32_e32 v107, v2
	v_mov_b32_e32 v108, v2
	v_mov_b32_e32 v109, v2
	v_mov_b32_e32 v114, v2
	v_mov_b32_e32 v115, v2
	v_mov_b32_e32 v116, v2
	v_mov_b32_e32 v117, v2
	v_mov_b32_e32 v122, v2
	v_mov_b32_e32 v123, v2
	v_mov_b32_e32 v124, v2
	v_mov_b32_e32 v125, v2
	v_mov_b32_e32 v70, v2
	v_mov_b32_e32 v71, v2
	v_mov_b32_e32 v72, v2
	v_mov_b32_e32 v73, v2
	v_mov_b32_e32 v78, v2
	v_mov_b32_e32 v79, v2
	v_mov_b32_e32 v80, v2
	v_mov_b32_e32 v81, v2
	v_mov_b32_e32 v86, v2
	v_mov_b32_e32 v87, v2
	v_mov_b32_e32 v88, v2
	v_mov_b32_e32 v89, v2
	v_mov_b32_e32 v94, v2
	v_mov_b32_e32 v95, v2
	v_mov_b32_e32 v96, v2
	v_mov_b32_e32 v97, v2
	v_mov_b32_e32 v102, v2
	v_mov_b32_e32 v103, v2
	v_mov_b32_e32 v104, v2
	v_mov_b32_e32 v105, v2
	v_mov_b32_e32 v110, v2
	v_mov_b32_e32 v111, v2
	v_mov_b32_e32 v112, v2
	v_mov_b32_e32 v113, v2
	v_mov_b32_e32 v118, v2
	v_mov_b32_e32 v119, v2
	v_mov_b32_e32 v120, v2
	v_mov_b32_e32 v121, v2
	v_mov_b32_e32 v126, v2
	v_mov_b32_e32 v127, v2
	v_mov_b32_e32 v128, v2
	v_mov_b32_e32 v129, v2
	s_nop 0
.LBB0_1149:
	s_add_u32 s34, s46, 0xfffc0080
	s_addc_u32 s35, s47, -1
	s_add_i32 s67, 0, 0x10000
	s_cmp_eq_u32 s66, 12
	s_cselect_b32 s51, s37, s35
	s_cselect_b32 s50, s62, s34
	s_cselect_b32 s49, s27, s65
	s_cselect_b32 s48, s63, s64
	s_add_i32 s34, 0, 0x14000
	v_add_u32_e32 v156, s67, v160
	v_add_u32_e32 v163, s34, v160
	ds_read_b128 v[144:147], v156
	ds_read_b128 v[148:151], v156 offset:1024
	ds_read_b128 v[152:155], v156 offset:2048
	ds_read_b128 v[156:159], v156 offset:3072
	ds_read_b128 v[164:167], v163
	ds_read_b128 v[168:171], v163 offset:1024
	ds_read_b128 v[172:175], v163 offset:2048
	ds_read_b128 v[176:179], v163 offset:3072
	v_lshl_add_u64 v[212:213], s[46:47], 0, v[140:141]
	s_add_i32 m0, s45, 0xc000
	ds_read_b128 v[180:183], v162
	ds_read_b128 v[184:187], v162 offset:1024
	ds_read_b128 v[188:191], v162 offset:2048
	ds_read_b128 v[192:195], v162 offset:3072
	ds_read_b128 v[196:199], v162 offset:4096
	ds_read_b128 v[200:203], v162 offset:5120
	ds_read_b128 v[204:207], v162 offset:6144
	ds_read_b128 v[208:211], v162 offset:7168
	global_load_lds_dwordx4 v[212:213], off
	v_lshl_add_u64 v[212:213], s[46:47], 0, v[142:143]
	s_add_i32 m0, s45, 0xe000
	s_nop 0
	global_load_lds_dwordx4 v[212:213], off
	s_waitcnt vmcnt(8)
	s_waitcnt lgkmcnt(0)
	s_barrier
; #define PG8_STAGE(bufoff, gbase, voff) do { _Pragma("unroll") for (int _i = 0; _i < 2; ++_i) \
;         __builtin_amdgcn_global_load_lds((const unsigned*)((const char*)(gbase) + (voff)[_i]), (PG8_LAS unsigned*)(lds + (bufoff) + ldsw + _i * 8192), 16, 0, 0); } while (0)
; #define PG8_LDA(dst, b, h) do { _Pragma("unroll") for (int m = 0; m < 4; ++m) _Pragma("unroll") for (int k = 0; k < 2; ++k) dst[m][k] = *(const PG8_LAS bf16x8*)(lds + PG8_SA(b, h) + aoff + m * 2048 + k * 1024); } while (0)
; #define PG8_MMA(ai, bj, At, Bt) do { __builtin_amdgcn_s_setprio(1); _Pragma("unroll") for (int m = 0; m < 4; ++m) _Pragma("unroll") for (int n = 0; n < 2; ++n) _Pragma("unroll") for (int k = 0; k < 2; ++k) \
;         acc[ai][bj][m][n] = __builtin_amdgcn_mfma_f32_16x16x32_bf16(Bt[n][k], At[m][k], acc[ai][bj][m][n], 0, 0, 0); __builtin_amdgcn_s_setprio(0); } while (0)
; #define PG8_WAIT_V(n) asm volatile("s_waitcnt vmcnt(" #n ")" ::: "memory")
; #define PG8_WAIT_L(n) asm volatile("s_waitcnt lgkmcnt(" #n ")" ::: "memory")
; #define PG8_BAR __builtin_amdgcn_s_barrier()
; #define PG8_SCHED __builtin_amdgcn_sched_barrier(0)
; template <class Epi, class Sched, bool ALIGN_EPI = false, bool SP2 = false>
; __device__ __forceinline__ void gemm_phase(PG8_LAS unsigned char* lds, const Gemm g, const Sched& S, const Epi& E) {
;     ...
;             PG8_WAIT_V(8); PG8_WAIT_L(0); PG8_BAR; PG8_MMA(0, 0, At, B0); PG8_MMA(0, 1, At, B1); PG8_BAR; PG8_SCHED;
;             PG8_LDA(At, 0, 1); PG8_STAGE(PG8_SB(0, 0), b2, voffB); PG8_STAGE(PG8_SB(0, 1), b2 + hstep, voffB); PG8_STAGE(PG8_SA(0, 0), a2, voffA);
;             PG8_WAIT_V(8); PG8_WAIT_L(0); PG8_BAR; PG8_MMA(1, 0, At, B0); PG8_MMA(1, 1, At, B1); PG8_BAR; PG8_SCHED;
	s_setprio 1
	s_waitcnt lgkmcnt(0)
	v_mfma_f32_16x16x32_bf16 v[126:129], v[144:147], v[180:183], v[126:129]
	v_mfma_f32_16x16x32_bf16 v[118:121], v[152:155], v[180:183], v[118:121]
	v_mfma_f32_16x16x32_bf16 v[110:113], v[144:147], v[188:191], v[110:113]
	v_mfma_f32_16x16x32_bf16 v[102:105], v[152:155], v[188:191], v[102:105]
	v_mfma_f32_16x16x32_bf16 v[94:97], v[144:147], v[196:199], v[94:97]
	v_mfma_f32_16x16x32_bf16 v[86:89], v[152:155], v[196:199], v[86:89]
	v_mfma_f32_16x16x32_bf16 v[78:81], v[144:147], v[204:207], v[78:81]
	v_mfma_f32_16x16x32_bf16 v[70:73], v[152:155], v[204:207], v[70:73]
	v_mfma_f32_16x16x32_bf16 v[126:129], v[148:151], v[184:187], v[126:129]
	v_mfma_f32_16x16x32_bf16 v[118:121], v[156:159], v[184:187], v[118:121]
	v_mfma_f32_16x16x32_bf16 v[110:113], v[148:151], v[192:195], v[110:113]
	v_mfma_f32_16x16x32_bf16 v[102:105], v[156:159], v[192:195], v[102:105]
	v_mfma_f32_16x16x32_bf16 v[94:97], v[148:151], v[200:203], v[94:97]
	v_mfma_f32_16x16x32_bf16 v[86:89], v[156:159], v[200:203], v[86:89]
	v_mfma_f32_16x16x32_bf16 v[78:81], v[148:151], v[208:211], v[78:81]
	v_mfma_f32_16x16x32_bf16 v[70:73], v[156:159], v[208:211], v[70:73]
	s_setprio 0
	s_setprio 1
	v_mfma_f32_16x16x32_bf16 v[122:125], v[164:167], v[180:183], v[122:125]
	v_mfma_f32_16x16x32_bf16 v[114:117], v[172:175], v[180:183], v[114:117]
	v_mfma_f32_16x16x32_bf16 v[106:109], v[164:167], v[188:191], v[106:109]
	v_mfma_f32_16x16x32_bf16 v[98:101], v[172:175], v[188:191], v[98:101]
	v_mfma_f32_16x16x32_bf16 v[90:93], v[164:167], v[196:199], v[90:93]
	v_mfma_f32_16x16x32_bf16 v[82:85], v[172:175], v[196:199], v[82:85]
	v_mfma_f32_16x16x32_bf16 v[74:77], v[164:167], v[204:207], v[74:77]
	v_mfma_f32_16x16x32_bf16 v[66:69], v[172:175], v[204:207], v[66:69]
	v_mfma_f32_16x16x32_bf16 v[122:125], v[168:171], v[184:187], v[122:125]
	v_mfma_f32_16x16x32_bf16 v[114:117], v[176:179], v[184:187], v[114:117]
	v_mfma_f32_16x16x32_bf16 v[106:109], v[168:171], v[192:195], v[106:109]
	v_mfma_f32_16x16x32_bf16 v[98:101], v[176:179], v[192:195], v[98:101]
	v_mfma_f32_16x16x32_bf16 v[90:93], v[168:171], v[200:203], v[90:93]
	v_mfma_f32_16x16x32_bf16 v[82:85], v[176:179], v[200:203], v[82:85]
	v_mfma_f32_16x16x32_bf16 v[74:77], v[168:171], v[208:211], v[74:77]
	v_mfma_f32_16x16x32_bf16 v[66:69], v[176:179], v[208:211], v[66:69]
	s_setprio 0
	s_barrier
	s_add_i32 s35, s67, s22
	v_lshl_add_u64 v[212:213], s[48:49], 0, v[134:135]
	s_mov_b32 m0, s35
	ds_read_b128 v[180:183], v162 offset:16384
	ds_read_b128 v[184:187], v162 offset:17408
	ds_read_b128 v[188:191], v162 offset:18432
	ds_read_b128 v[192:195], v162 offset:19456
	ds_read_b128 v[196:199], v162 offset:20480
	ds_read_b128 v[200:203], v162 offset:21504
	ds_read_b128 v[204:207], v162 offset:22528
	ds_read_b128 v[208:211], v162 offset:23552
	global_load_lds_dwordx4 v[212:213], off
	s_add_i32 m0, s35, 0x2000
	s_add_u32 s68, s48, 0x40000
	v_lshl_add_u64 v[214:215], s[48:49], 0, v[130:131]
	s_addc_u32 s69, s49, 0
	s_add_i32 s34, s34, s22
	global_load_lds_dwordx4 v[214:215], off
	v_lshl_add_u64 v[216:217], s[68:69], 0, v[134:135]
	s_mov_b32 m0, s34
	v_lshl_add_u64 v[218:219], s[50:51], 0, v[132:133]
	global_load_lds_dwordx4 v[216:217], off
	v_lshl_add_u64 v[216:217], s[68:69], 0, v[130:131]
	s_add_i32 m0, s34, 0x2000
	s_nop 0
	global_load_lds_dwordx4 v[216:217], off
	v_lshl_add_u64 v[216:217], s[50:51], 0, v[136:137]
	s_mov_b32 m0, s45
	s_nop 0
	global_load_lds_dwordx4 v[216:217], off
	s_mov_b32 m0, s55
	s_nop 0
	global_load_lds_dwordx4 v[218:219], off
	s_waitcnt vmcnt(8)
	s_waitcnt lgkmcnt(0)
	s_barrier
	s_setprio 1
	s_waitcnt lgkmcnt(0)
	v_mfma_f32_16x16x32_bf16 v[62:65], v[144:147], v[180:183], v[62:65]
	v_mfma_f32_16x16x32_bf16 v[54:57], v[152:155], v[180:183], v[54:57]
	v_mfma_f32_16x16x32_bf16 v[46:49], v[144:147], v[188:191], v[46:49]
	v_mfma_f32_16x16x32_bf16 v[38:41], v[152:155], v[188:191], v[38:41]
	v_mfma_f32_16x16x32_bf16 v[30:33], v[144:147], v[196:199], v[30:33]
	v_mfma_f32_16x16x32_bf16 v[22:25], v[152:155], v[196:199], v[22:25]
	v_mfma_f32_16x16x32_bf16 v[14:17], v[144:147], v[204:207], v[14:17]
	v_mfma_f32_16x16x32_bf16 v[6:9], v[152:155], v[204:207], v[6:9]
	v_mfma_f32_16x16x32_bf16 v[62:65], v[148:151], v[184:187], v[62:65]
	v_mfma_f32_16x16x32_bf16 v[54:57], v[156:159], v[184:187], v[54:57]
	v_mfma_f32_16x16x32_bf16 v[46:49], v[148:151], v[192:195], v[46:49]
	v_mfma_f32_16x16x32_bf16 v[38:41], v[156:159], v[192:195], v[38:41]
	v_mfma_f32_16x16x32_bf16 v[30:33], v[148:151], v[200:203], v[30:33]
	v_mfma_f32_16x16x32_bf16 v[22:25], v[156:159], v[200:203], v[22:25]
	v_mfma_f32_16x16x32_bf16 v[14:17], v[148:151], v[208:211], v[14:17]
	v_mfma_f32_16x16x32_bf16 v[6:9], v[156:159], v[208:211], v[6:9]
	s_setprio 0
	s_setprio 1
	v_mfma_f32_16x16x32_bf16 v[58:61], v[164:167], v[180:183], v[58:61]
	v_mfma_f32_16x16x32_bf16 v[50:53], v[172:175], v[180:183], v[50:53]
	v_mfma_f32_16x16x32_bf16 v[42:45], v[164:167], v[188:191], v[42:45]
	v_mfma_f32_16x16x32_bf16 v[34:37], v[172:175], v[188:191], v[34:37]
	v_mfma_f32_16x16x32_bf16 v[26:29], v[164:167], v[196:199], v[26:29]
	v_mfma_f32_16x16x32_bf16 v[18:21], v[172:175], v[196:199], v[18:21]
	v_mfma_f32_16x16x32_bf16 v[10:13], v[164:167], v[204:207], v[10:13]
	v_mfma_f32_16x16x32_bf16 v[2:5], v[172:175], v[204:207], v[2:5]
	v_mfma_f32_16x16x32_bf16 v[58:61], v[168:171], v[184:187], v[58:61]
	v_mfma_f32_16x16x32_bf16 v[50:53], v[176:179], v[184:187], v[50:53]
	v_mfma_f32_16x16x32_bf16 v[42:45], v[168:171], v[192:195], v[42:45]
	v_mfma_f32_16x16x32_bf16 v[34:37], v[176:179], v[192:195], v[34:37]
	v_mfma_f32_16x16x32_bf16 v[26:29], v[168:171], v[200:203], v[26:29]
	v_mfma_f32_16x16x32_bf16 v[18:21], v[176:179], v[200:203], v[18:21]
	v_mfma_f32_16x16x32_bf16 v[10:13], v[168:171], v[208:211], v[10:13]
	v_mfma_f32_16x16x32_bf16 v[2:5], v[176:179], v[208:211], v[2:5]
	s_setprio 0
	s_barrier
; #define PG8_STAGE(bufoff, gbase, voff) do { _Pragma("unroll") for (int _i = 0; _i < 2; ++_i) \
;         __builtin_amdgcn_global_load_lds((const unsigned*)((const char*)(gbase) + (voff)[_i]), (PG8_LAS unsigned*)(lds + (bufoff) + ldsw + _i * 8192), 16, 0, 0); } while (0)
; #define PG8_LDA(dst, b, h) do { _Pragma("unroll") for (int m = 0; m < 4; ++m) _Pragma("unroll") for (int k = 0; k < 2; ++k) dst[m][k] = *(const PG8_LAS bf16x8*)(lds + PG8_SA(b, h) + aoff + m * 2048 + k * 1024); } while (0)
; #define PG8_LDB(dst, b, h) do { _Pragma("unroll") for (int n = 0; n < 2; ++n) _Pragma("unroll") for (int k = 0; k < 2; ++k) dst[n][k] = *(const PG8_LAS bf16x8*)(lds + PG8_SB(b, h) + boff + n * 2048 + k * 1024); } while (0)
; #define PG8_MMA(ai, bj, At, Bt) do { __builtin_amdgcn_s_setprio(1); _Pragma("unroll") for (int m = 0; m < 4; ++m) _Pragma("unroll") for (int n = 0; n < 2; ++n) _Pragma("unroll") for (int k = 0; k < 2; ++k) \
;         acc[ai][bj][m][n] = __builtin_amdgcn_mfma_f32_16x16x32_bf16(Bt[n][k], At[m][k], acc[ai][bj][m][n], 0, 0, 0); __builtin_amdgcn_s_setprio(0); } while (0)
; #define PG8_WAIT_V(n) asm volatile("s_waitcnt vmcnt(" #n ")" ::: "memory")
; #define PG8_WAIT_L(n) asm volatile("s_waitcnt lgkmcnt(" #n ")" ::: "memory")
; #define PG8_BAR __builtin_amdgcn_s_barrier()
; #define PG8_SCHED __builtin_amdgcn_sched_barrier(0)
; template <class Epi, class Sched, bool ALIGN_EPI = false, bool SP2 = false>
; __device__ __forceinline__ void gemm_phase(PG8_LAS unsigned char* lds, const Gemm g, const Sched& S, const Epi& E) {
;     ...
;             PG8_LDB(B0, 1, 0); PG8_LDB(B1, 1, 1); PG8_SCHED; PG8_LDA(At, 1, 0); PG8_STAGE(PG8_SA(0, 1), a2 + hstepA, voffA);
;             PG8_WAIT_V(8); PG8_WAIT_L(0); PG8_BAR; PG8_MMA(0, 0, At, B0); PG8_MMA(0, 1, At, B1); PG8_BAR; PG8_SCHED;
	s_add_i32 s34, 0, 0x18000
	s_add_i32 s35, 0, 0x1c000
	v_add_u32_e32 v156, s34, v160
	v_add_u32_e32 v163, s35, v160
	ds_read_b128 v[144:147], v156
	ds_read_b128 v[148:151], v156 offset:1024
	ds_read_b128 v[152:155], v156 offset:2048
	ds_read_b128 v[156:159], v156 offset:3072
	ds_read_b128 v[164:167], v163
	ds_read_b128 v[168:171], v163 offset:1024
	ds_read_b128 v[172:175], v163 offset:2048
	ds_read_b128 v[176:179], v163 offset:3072
	s_add_u32 s50, s50, 0x40000
	s_addc_u32 s51, s51, 0
	s_mov_b32 m0, s56
	v_lshl_add_u64 v[220:221], s[50:51], 0, v[136:137]
	ds_read_b128 v[180:183], v162 offset:32768
	ds_read_b128 v[184:187], v162 offset:33792
	ds_read_b128 v[188:191], v162 offset:34816
	ds_read_b128 v[192:195], v162 offset:35840
	ds_read_b128 v[196:199], v162 offset:36864
	ds_read_b128 v[200:203], v162 offset:37888
	ds_read_b128 v[204:207], v162 offset:38912
	ds_read_b128 v[208:211], v162 offset:39936
	global_load_lds_dwordx4 v[220:221], off
	v_lshl_add_u64 v[220:221], s[50:51], 0, v[132:133]
	s_mov_b32 m0, s57
	s_nop 0
	global_load_lds_dwordx4 v[220:221], off
	s_waitcnt vmcnt(8)
	s_waitcnt lgkmcnt(0)
	s_barrier
	s_setprio 1
	s_waitcnt lgkmcnt(0)
	v_mfma_f32_16x16x32_bf16 v[126:129], v[144:147], v[180:183], v[126:129]
	v_mfma_f32_16x16x32_bf16 v[118:121], v[152:155], v[180:183], v[118:121]
	v_mfma_f32_16x16x32_bf16 v[110:113], v[144:147], v[188:191], v[110:113]
	v_mfma_f32_16x16x32_bf16 v[102:105], v[152:155], v[188:191], v[102:105]
	v_mfma_f32_16x16x32_bf16 v[94:97], v[144:147], v[196:199], v[94:97]
	v_mfma_f32_16x16x32_bf16 v[86:89], v[152:155], v[196:199], v[86:89]
	v_mfma_f32_16x16x32_bf16 v[78:81], v[144:147], v[204:207], v[78:81]
	v_mfma_f32_16x16x32_bf16 v[70:73], v[152:155], v[204:207], v[70:73]
	v_mfma_f32_16x16x32_bf16 v[126:129], v[148:151], v[184:187], v[126:129]
	v_mfma_f32_16x16x32_bf16 v[118:121], v[156:159], v[184:187], v[118:121]
	v_mfma_f32_16x16x32_bf16 v[110:113], v[148:151], v[192:195], v[110:113]
	v_mfma_f32_16x16x32_bf16 v[102:105], v[156:159], v[192:195], v[102:105]
	v_mfma_f32_16x16x32_bf16 v[94:97], v[148:151], v[200:203], v[94:97]
	v_mfma_f32_16x16x32_bf16 v[86:89], v[156:159], v[200:203], v[86:89]
	v_mfma_f32_16x16x32_bf16 v[78:81], v[148:151], v[208:211], v[78:81]
	v_mfma_f32_16x16x32_bf16 v[70:73], v[156:159], v[208:211], v[70:73]
	s_setprio 0
	s_setprio 1
	v_mfma_f32_16x16x32_bf16 v[122:125], v[164:167], v[180:183], v[122:125]
	v_mfma_f32_16x16x32_bf16 v[114:117], v[172:175], v[180:183], v[114:117]
	v_mfma_f32_16x16x32_bf16 v[106:109], v[164:167], v[188:191], v[106:109]
	v_mfma_f32_16x16x32_bf16 v[98:101], v[172:175], v[188:191], v[98:101]
	v_mfma_f32_16x16x32_bf16 v[90:93], v[164:167], v[196:199], v[90:93]
	v_mfma_f32_16x16x32_bf16 v[82:85], v[172:175], v[196:199], v[82:85]
	v_mfma_f32_16x16x32_bf16 v[74:77], v[164:167], v[204:207], v[74:77]
	v_mfma_f32_16x16x32_bf16 v[66:69], v[172:175], v[204:207], v[66:69]
	v_mfma_f32_16x16x32_bf16 v[122:125], v[168:171], v[184:187], v[122:125]
	v_mfma_f32_16x16x32_bf16 v[114:117], v[176:179], v[184:187], v[114:117]
	v_mfma_f32_16x16x32_bf16 v[106:109], v[168:171], v[192:195], v[106:109]
	v_mfma_f32_16x16x32_bf16 v[98:101], v[176:179], v[192:195], v[98:101]
	v_mfma_f32_16x16x32_bf16 v[90:93], v[168:171], v[200:203], v[90:93]
	v_mfma_f32_16x16x32_bf16 v[82:85], v[176:179], v[200:203], v[82:85]
	v_mfma_f32_16x16x32_bf16 v[74:77], v[168:171], v[208:211], v[74:77]
	v_mfma_f32_16x16x32_bf16 v[66:69], v[176:179], v[208:211], v[66:69]
	s_setprio 0
	s_barrier
; #define PG8_STAGE(bufoff, gbase, voff) do { _Pragma("unroll") for (int _i = 0; _i < 2; ++_i) \
;         __builtin_amdgcn_global_load_lds((const unsigned*)((const char*)(gbase) + (voff)[_i]), (PG8_LAS unsigned*)(lds + (bufoff) + ldsw + _i * 8192), 16, 0, 0); } while (0)
; #define PG8_LDA(dst, b, h) do { _Pragma("unroll") for (int m = 0; m < 4; ++m) _Pragma("unroll") for (int k = 0; k < 2; ++k) dst[m][k] = *(const PG8_LAS bf16x8*)(lds + PG8_SA(b, h) + aoff + m * 2048 + k * 1024); } while (0)
; #define PG8_MMA(ai, bj, At, Bt) do { __builtin_amdgcn_s_setprio(1); _Pragma("unroll") for (int m = 0; m < 4; ++m) _Pragma("unroll") for (int n = 0; n < 2; ++n) _Pragma("unroll") for (int k = 0; k < 2; ++k) \
;         acc[ai][bj][m][n] = __builtin_amdgcn_mfma_f32_16x16x32_bf16(Bt[n][k], At[m][k], acc[ai][bj][m][n], 0, 0, 0); __builtin_amdgcn_s_setprio(0); } while (0)
; #define PG8_WAIT_V(n) asm volatile("s_waitcnt vmcnt(" #n ")" ::: "memory")
; #define PG8_WAIT_L(n) asm volatile("s_waitcnt lgkmcnt(" #n ")" ::: "memory")
; #define PG8_BAR __builtin_amdgcn_s_barrier()
; #define PG8_SCHED __builtin_amdgcn_sched_barrier(0)
; template <class Epi, class Sched, bool ALIGN_EPI = false, bool SP2 = false>
; __device__ __forceinline__ void gemm_phase(PG8_LAS unsigned char* lds, const Gemm g, const Sched& S, const Epi& E) {
;     ...
;             PG8_LDA(At, 1, 1); PG8_STAGE(PG8_SB(1, 0), b3, voffB); PG8_STAGE(PG8_SB(1, 1), b3 + hstep, voffB); PG8_STAGE(PG8_SA(1, 0), a3, voffA);
;             PG8_WAIT_V(8); PG8_WAIT_L(0); PG8_BAR; PG8_MMA(1, 0, At, B0); PG8_MMA(1, 1, At, B1); PG8_BAR; PG8_SCHED;
	s_add_i32 s34, s34, s22
	v_lshl_add_u64 v[212:213], v[212:213], 0, s[12:13]
	s_mov_b32 m0, s34
	ds_read_b128 v[180:183], v162 offset:49152
	ds_read_b128 v[184:187], v162 offset:50176
	ds_read_b128 v[188:191], v162 offset:51200
	ds_read_b128 v[192:195], v162 offset:52224
	ds_read_b128 v[196:199], v162 offset:53248
	ds_read_b128 v[200:203], v162 offset:54272
	ds_read_b128 v[204:207], v162 offset:55296
	ds_read_b128 v[208:211], v162 offset:56320
	global_load_lds_dwordx4 v[212:213], off
	s_add_i32 m0, s34, 0x2000
	s_add_u32 s48, s48, 0x40080
	v_lshl_add_u64 v[212:213], v[214:215], 0, s[12:13]
	s_addc_u32 s49, s49, 0
	s_add_i32 s34, s35, s22
	global_load_lds_dwordx4 v[212:213], off
	v_lshl_add_u64 v[212:213], s[48:49], 0, v[134:135]
	s_mov_b32 m0, s34
	s_nop 0
	global_load_lds_dwordx4 v[212:213], off
	v_lshl_add_u64 v[212:213], s[48:49], 0, v[130:131]
	s_add_i32 m0, s34, 0x2000
	s_nop 0
	global_load_lds_dwordx4 v[212:213], off
	v_lshl_add_u64 v[212:213], v[216:217], 0, s[12:13]
	s_mov_b32 m0, s58
	s_nop 0
	global_load_lds_dwordx4 v[212:213], off
	v_lshl_add_u64 v[212:213], v[218:219], 0, s[12:13]
	s_mov_b32 m0, s59
	s_nop 0
	global_load_lds_dwordx4 v[212:213], off
	s_waitcnt vmcnt(8)
	s_waitcnt lgkmcnt(0)
	s_barrier
	s_setprio 1
	s_waitcnt lgkmcnt(0)
	v_mfma_f32_16x16x32_bf16 v[62:65], v[144:147], v[180:183], v[62:65]
	v_mfma_f32_16x16x32_bf16 v[54:57], v[152:155], v[180:183], v[54:57]
	v_mfma_f32_16x16x32_bf16 v[46:49], v[144:147], v[188:191], v[46:49]
	v_mfma_f32_16x16x32_bf16 v[38:41], v[152:155], v[188:191], v[38:41]
	v_mfma_f32_16x16x32_bf16 v[30:33], v[144:147], v[196:199], v[30:33]
	v_mfma_f32_16x16x32_bf16 v[22:25], v[152:155], v[196:199], v[22:25]
	v_mfma_f32_16x16x32_bf16 v[14:17], v[144:147], v[204:207], v[14:17]
	v_mfma_f32_16x16x32_bf16 v[6:9], v[152:155], v[204:207], v[6:9]
	v_mfma_f32_16x16x32_bf16 v[62:65], v[148:151], v[184:187], v[62:65]
	v_mfma_f32_16x16x32_bf16 v[54:57], v[156:159], v[184:187], v[54:57]
	v_mfma_f32_16x16x32_bf16 v[46:49], v[148:151], v[192:195], v[46:49]
	v_mfma_f32_16x16x32_bf16 v[38:41], v[156:159], v[192:195], v[38:41]
	v_mfma_f32_16x16x32_bf16 v[30:33], v[148:151], v[200:203], v[30:33]
	v_mfma_f32_16x16x32_bf16 v[22:25], v[156:159], v[200:203], v[22:25]
	v_mfma_f32_16x16x32_bf16 v[14:17], v[148:151], v[208:211], v[14:17]
	v_mfma_f32_16x16x32_bf16 v[6:9], v[156:159], v[208:211], v[6:9]
	s_setprio 0
	s_setprio 1
	v_mfma_f32_16x16x32_bf16 v[58:61], v[164:167], v[180:183], v[58:61]
	v_mfma_f32_16x16x32_bf16 v[50:53], v[172:175], v[180:183], v[50:53]
	v_mfma_f32_16x16x32_bf16 v[42:45], v[164:167], v[188:191], v[42:45]
	v_mfma_f32_16x16x32_bf16 v[34:37], v[172:175], v[188:191], v[34:37]
	v_mfma_f32_16x16x32_bf16 v[26:29], v[164:167], v[196:199], v[26:29]
	v_mfma_f32_16x16x32_bf16 v[18:21], v[172:175], v[196:199], v[18:21]
	v_mfma_f32_16x16x32_bf16 v[10:13], v[164:167], v[204:207], v[10:13]
	v_mfma_f32_16x16x32_bf16 v[2:5], v[172:175], v[204:207], v[2:5]
	v_mfma_f32_16x16x32_bf16 v[58:61], v[168:171], v[184:187], v[58:61]
	v_mfma_f32_16x16x32_bf16 v[50:53], v[176:179], v[184:187], v[50:53]
	v_mfma_f32_16x16x32_bf16 v[42:45], v[168:171], v[192:195], v[42:45]
	v_mfma_f32_16x16x32_bf16 v[34:37], v[176:179], v[192:195], v[34:37]
	v_mfma_f32_16x16x32_bf16 v[26:29], v[168:171], v[200:203], v[26:29]
	v_mfma_f32_16x16x32_bf16 v[18:21], v[176:179], v[200:203], v[18:21]
	v_mfma_f32_16x16x32_bf16 v[10:13], v[168:171], v[208:211], v[10:13]
	v_mfma_f32_16x16x32_bf16 v[2:5], v[176:179], v[208:211], v[2:5]
	s_setprio 0
	s_barrier
	s_add_i32 s66, s66, 2
	s_add_u32 s46, s46, 0x100
	s_addc_u32 s47, s47, 0
	s_add_u32 s64, s64, 0x100
	s_addc_u32 s65, s65, 0
	s_cmp_gt_u32 s66, 13
	s_cbranch_scc0 .LBB0_1149
	s_nop 0
	s_and_b64 vcc, exec, s[20:21]
	s_cbranch_vccz .LBB0_1152
	s_barrier
